# v81 + mixer-A token loop: loop-entry vmcnt waits moved to the pre-header so the back edge no longer waits for the previous iteration's stores before issuing loads
# speedup vs baseline: 1.0040x; 1.0040x over previous
.LBB0_648:
	s_and_b32 s22, s34, 0x200
	v_or_b32_e32 v36, s22, v74
	s_and_b64 s[22:23], s[24:25], exec
	s_cselect_b32 s22, s14, s47
	s_ashr_i32 s23, s22, 31
	s_lshl_b64 s[48:49], s[22:23], 13
	s_and_b64 s[22:23], s[24:25], exec
	s_cselect_b32 s14, 0, 31
	s_cmp_eq_u32 s46, s14
	s_cselect_b64 s[22:23], -1, 0
	s_ashr_i32 s27, s26, 31
	s_lshl_b64 s[26:27], s[26:27], 11
	s_add_u32 s26, s30, s26
	s_addc_u32 s27, s31, s27
	s_and_b64 s[24:25], s[24:25], exec
	s_cselect_b32 s14, s38, 0x8400000
	s_add_u32 s14, s48, s14
	s_addc_u32 s25, s49, 0
	s_add_u32 s24, s36, s14
	v_lshlrev_b32_e32 v64, 1, v36
	v_lshlrev_b32_e32 v36, 2, v36
	v_mov_b32_e32 v37, v65
	s_addc_u32 s25, s37, s25
	v_lshl_add_u64 v[66:67], s[26:27], 0, v[64:65]
	v_lshl_add_u64 v[68:69], s[24:25], 0, v[36:37]
	s_mov_b32 s14, -8
	s_waitcnt vmcnt(0)
	s_branch .LBB0_650

.LBB0_650:
	v_lshl_add_u64 v[44:45], v[66:67], 0, s[20:21]
	v_add_co_u32_e32 v36, vcc, s39, v44
	v_pk_mul_f32 v[42:43], v[6:7], v[42:43]
	v_addc_co_u32_e32 v37, vcc, -1, v45, vcc
	v_add_co_u32_e32 v108, vcc, s40, v66
	global_load_dwordx4 v[76:79], v[36:37], off offset:-2048
	s_nop 0
	v_addc_co_u32_e32 v109, vcc, -1, v67, vcc
	v_add_co_u32_e32 v46, vcc, s41, v44
	global_load_dwordx4 v[80:83], v[108:109], off offset:-2048
	s_nop 0
	v_addc_co_u32_e32 v47, vcc, -1, v45, vcc
	v_add_co_u32_e32 v72, vcc, s42, v66
	global_load_dwordx4 v[84:87], v[46:47], off offset:-4096
	s_nop 0
	v_addc_co_u32_e32 v73, vcc, -1, v67, vcc
	global_load_dwordx4 v[88:91], v[72:73], off offset:-4096
	global_load_dwordx4 v[48:51], v[66:67], off offset:-2048
	global_load_dwordx4 v[36:39], v[66:67], off
	global_load_dwordx4 v[92:95], v[72:73], off offset:-2048
	global_load_dwordx4 v[96:99], v[72:73], off
	global_load_dwordx4 v[100:103], v[46:47], off offset:-2048
	v_add_co_u32_e32 v70, vcc, s44, v66
	v_pk_mul_f32 v[40:41], v[4:5], v[40:41]
	s_nop 0
	v_addc_co_u32_e32 v71, vcc, -1, v67, vcc
	v_add_co_u32_e32 v52, vcc, s43, v44
	v_pk_mul_f32 v[34:35], v[2:3], v[34:35]
	v_addc_co_u32_e32 v53, vcc, -1, v45, vcc
	v_add_co_u32_e32 v44, vcc, s45, v44
	v_pk_mul_f32 v[32:33], v[0:1], v[32:33]
	s_nop 0
	v_addc_co_u32_e32 v45, vcc, -1, v45, vcc
	v_pk_fma_f32 v[110:111], v[14:15], v[30:31], v[42:43]
	v_pk_fma_f32 v[112:113], v[12:13], v[28:29], v[40:41]
	v_pk_fma_f32 v[114:115], v[10:11], v[26:27], v[34:35]
	v_pk_fma_f32 v[116:117], v[8:9], v[24:25], v[32:33]
	global_load_dwordx4 v[104:107], v[46:47], off
	global_load_dwordx4 v[60:63], v[52:53], off offset:-2048
	global_load_dwordx4 v[56:59], v[70:71], off offset:-2048
	s_nop 0
	global_load_dwordx4 v[52:55], v[44:45], off offset:-4096
	global_load_dwordx4 v[32:35], v[44:45], off offset:-2048
	global_load_dwordx4 v[40:43], v[66:67], off offset:-4096
	s_nop 0
	global_load_dwordx4 v[44:47], v[44:45], off
	s_add_i32 s24, s14, 14
	s_cmp_gt_u32 s24, 61
	s_cselect_b64 s[24:25], -1, 0
	s_and_b64 s[24:25], s[22:23], s[24:25]
	s_andn2_b64 vcc, exec, s[24:25]
	s_waitcnt vmcnt(15)
	v_lshlrev_b32_e32 v118, 16, v76
	v_and_b32_e32 v119, 0xffff0000, v76
	v_lshlrev_b32_e32 v120, 16, v77
	v_and_b32_e32 v121, 0xffff0000, v77
	v_lshlrev_b32_e32 v122, 16, v78
	v_and_b32_e32 v123, 0xffff0000, v78
	v_lshlrev_b32_e32 v124, 16, v79
	v_and_b32_e32 v125, 0xffff0000, v79
	s_waitcnt vmcnt(14)
	v_lshlrev_b32_e32 v76, 16, v80
	v_and_b32_e32 v77, 0xffff0000, v80
	v_lshlrev_b32_e32 v78, 16, v81
	v_and_b32_e32 v79, 0xffff0000, v81
	v_pk_fma_f32 v[112:113], v[20:21], v[118:119], v[112:113]
	v_pk_fma_f32 v[110:111], v[22:23], v[120:121], v[110:111]
	v_lshlrev_b32_e32 v80, 16, v82
	v_and_b32_e32 v81, 0xffff0000, v82
	v_lshlrev_b32_e32 v82, 16, v83
	v_and_b32_e32 v83, 0xffff0000, v83
	v_pk_fma_f32 v[116:117], v[16:17], v[122:123], v[116:117]
	v_pk_fma_f32 v[114:115], v[18:19], v[124:125], v[114:115]
	v_pk_mul_f32 v[78:79], v[110:111], v[78:79]
	v_pk_mul_f32 v[76:77], v[112:113], v[76:77]
	v_pk_mul_f32 v[82:83], v[114:115], v[82:83]
	v_pk_mul_f32 v[80:81], v[116:117], v[80:81]
	v_cvt_pk_bf16_f32 v76, v76, v77
	v_cvt_pk_bf16_f32 v77, v78, v79
	s_waitcnt vmcnt(13)
	v_lshlrev_b32_e32 v128, 16, v86
	v_cvt_pk_bf16_f32 v78, v80, v81
	v_cvt_pk_bf16_f32 v79, v82, v83
	global_store_dwordx4 v[108:109], v[76:79], off offset:-2048
	v_and_b32_e32 v129, 0xffff0000, v86
	s_waitcnt vmcnt(13)
	v_lshlrev_b32_e32 v80, 16, v89
	v_lshlrev_b32_e32 v76, 16, v87
	v_and_b32_e32 v77, 0xffff0000, v87
	v_lshlrev_b32_e32 v78, 16, v88
	v_and_b32_e32 v79, 0xffff0000, v88
	v_and_b32_e32 v81, 0xffff0000, v89
	v_lshlrev_b32_e32 v82, 16, v90
	v_and_b32_e32 v83, 0xffff0000, v90
	v_lshlrev_b32_e32 v86, 16, v91
	v_and_b32_e32 v87, 0xffff0000, v91
	v_pk_mul_f32 v[88:89], v[12:13], v[118:119]
	v_pk_mul_f32 v[90:91], v[14:15], v[120:121]
	v_lshlrev_b32_e32 v126, 16, v84
	v_and_b32_e32 v127, 0xffff0000, v84
	v_lshlrev_b32_e32 v84, 16, v85
	v_and_b32_e32 v85, 0xffff0000, v85
	v_pk_fma_f32 v[30:31], v[6:7], v[30:31], v[90:91]
	v_pk_fma_f32 v[28:29], v[4:5], v[28:29], v[88:89]
	v_pk_fma_f32 v[30:31], v[22:23], v[84:85], v[30:31]
	v_pk_fma_f32 v[28:29], v[20:21], v[126:127], v[28:29]
	v_pk_mul_f32 v[30:31], v[30:31], v[80:81]
	v_pk_mul_f32 v[28:29], v[28:29], v[78:79]
	v_pk_mul_f32 v[78:79], v[8:9], v[122:123]
	v_pk_mul_f32 v[80:81], v[10:11], v[124:125]
	v_pk_fma_f32 v[24:25], v[0:1], v[24:25], v[78:79]
	v_pk_fma_f32 v[26:27], v[2:3], v[26:27], v[80:81]
	v_pk_fma_f32 v[24:25], v[16:17], v[128:129], v[24:25]
	v_pk_fma_f32 v[26:27], v[18:19], v[76:77], v[26:27]
	v_pk_mul_f32 v[90:91], v[14:15], v[84:85]
	v_pk_mul_f32 v[78:79], v[26:27], v[86:87]
	v_pk_mul_f32 v[26:27], v[24:25], v[82:83]
	v_cvt_pk_bf16_f32 v24, v28, v29
	v_cvt_pk_bf16_f32 v25, v30, v31
	s_waitcnt vmcnt(8)
	v_lshlrev_b32_e32 v30, 16, v101
	v_cvt_pk_bf16_f32 v26, v26, v27
	v_cvt_pk_bf16_f32 v27, v78, v79
	v_and_b32_e32 v31, 0xffff0000, v101
	v_pk_mul_f32 v[88:89], v[12:13], v[126:127]
	v_pk_fma_f32 v[90:91], v[6:7], v[120:121], v[90:91]
	global_store_dwordx4 v[72:73], v[24:27], off offset:-4096
	v_lshlrev_b32_e32 v28, 16, v100
	v_and_b32_e32 v29, 0xffff0000, v100
	v_lshlrev_b32_e32 v26, 16, v93
	v_and_b32_e32 v27, 0xffff0000, v93
	v_pk_fma_f32 v[88:89], v[4:5], v[118:119], v[88:89]
	v_pk_fma_f32 v[90:91], v[22:23], v[30:31], v[90:91]
	v_lshlrev_b32_e32 v24, 16, v92
	v_and_b32_e32 v25, 0xffff0000, v92
	v_pk_fma_f32 v[88:89], v[20:21], v[28:29], v[88:89]
	v_pk_mul_f32 v[26:27], v[90:91], v[26:27]
	v_pk_mul_f32 v[90:91], v[10:11], v[76:77]
	v_lshlrev_b32_e32 v80, 16, v103
	v_and_b32_e32 v81, 0xffff0000, v103
	v_pk_mul_f32 v[24:25], v[88:89], v[24:25]
	v_pk_mul_f32 v[88:89], v[8:9], v[128:129]
	v_pk_fma_f32 v[90:91], v[2:3], v[124:125], v[90:91]
	v_lshlrev_b32_e32 v78, 16, v102
	v_and_b32_e32 v79, 0xffff0000, v102
	v_lshlrev_b32_e32 v86, 16, v95
	v_and_b32_e32 v87, 0xffff0000, v95
	v_pk_fma_f32 v[88:89], v[0:1], v[122:123], v[88:89]
	v_pk_fma_f32 v[90:91], v[18:19], v[80:81], v[90:91]
	v_lshlrev_b32_e32 v82, 16, v94
	v_and_b32_e32 v83, 0xffff0000, v94
	v_pk_fma_f32 v[88:89], v[16:17], v[78:79], v[88:89]
	v_pk_mul_f32 v[86:87], v[90:91], v[86:87]
	v_lshlrev_b32_e32 v92, 16, v98
	v_and_b32_e32 v93, 0xffff0000, v98
	v_lshlrev_b32_e32 v94, 16, v99
	v_and_b32_e32 v95, 0xffff0000, v99
	v_pk_mul_f32 v[98:99], v[14:15], v[30:31]
	v_pk_mul_f32 v[82:83], v[88:89], v[82:83]
	v_cvt_pk_bf16_f32 v24, v24, v25
	v_cvt_pk_bf16_f32 v25, v26, v27
	v_pk_fma_f32 v[84:85], v[6:7], v[84:85], v[98:99]
	v_cvt_pk_bf16_f32 v26, v82, v83
	v_cvt_pk_bf16_f32 v27, v86, v87
	s_waitcnt vmcnt(8)
	v_lshlrev_b32_e32 v86, 16, v105
	v_and_b32_e32 v87, 0xffff0000, v105
	global_store_dwordx4 v[72:73], v[24:27], off offset:-2048
	v_pk_fma_f32 v[84:85], v[22:23], v[86:87], v[84:85]
	v_lshlrev_b32_e32 v82, 16, v104
	v_lshlrev_b32_e32 v24, 16, v96
	v_and_b32_e32 v25, 0xffff0000, v96
	v_lshlrev_b32_e32 v26, 16, v97
	v_and_b32_e32 v27, 0xffff0000, v97
	v_pk_mul_f32 v[96:97], v[12:13], v[28:29]
	v_and_b32_e32 v83, 0xffff0000, v104
	v_pk_fma_f32 v[96:97], v[4:5], v[126:127], v[96:97]
	v_pk_mul_f32 v[26:27], v[84:85], v[26:27]
	v_pk_mul_f32 v[84:85], v[8:9], v[78:79]
	v_lshlrev_b32_e32 v88, 16, v106
	v_and_b32_e32 v89, 0xffff0000, v106
	v_pk_fma_f32 v[96:97], v[20:21], v[82:83], v[96:97]
	v_pk_fma_f32 v[84:85], v[0:1], v[128:129], v[84:85]
	v_pk_mul_f32 v[24:25], v[96:97], v[24:25]
	v_pk_mul_f32 v[96:97], v[10:11], v[80:81]
	v_pk_fma_f32 v[84:85], v[16:17], v[88:89], v[84:85]
	v_lshlrev_b32_e32 v90, 16, v107
	v_and_b32_e32 v91, 0xffff0000, v107
	v_pk_fma_f32 v[76:77], v[2:3], v[76:77], v[96:97]
	v_pk_mul_f32 v[84:85], v[84:85], v[92:93]
	v_pk_fma_f32 v[76:77], v[18:19], v[90:91], v[76:77]
	v_cvt_pk_bf16_f32 v24, v24, v25
	v_cvt_pk_bf16_f32 v25, v26, v27
	v_cvt_pk_bf16_f32 v26, v84, v85
	v_pk_mul_f32 v[84:85], v[12:13], v[82:83]
	v_pk_mul_f32 v[92:93], v[14:15], v[86:87]
	v_pk_mul_f32 v[76:77], v[76:77], v[94:95]
	v_pk_fma_f32 v[30:31], v[6:7], v[30:31], v[92:93]
	v_cvt_pk_bf16_f32 v27, v76, v77
	global_store_dwordx4 v[72:73], v[24:27], off
	s_waitcnt vmcnt(9)
	v_lshlrev_b32_e32 v72, 16, v60
	v_and_b32_e32 v73, 0xffff0000, v60
	v_lshlrev_b32_e32 v60, 16, v61
	v_and_b32_e32 v61, 0xffff0000, v61
	v_pk_fma_f32 v[28:29], v[4:5], v[28:29], v[84:85]
	s_waitcnt vmcnt(8)
	v_lshlrev_b32_e32 v24, 16, v56
	v_and_b32_e32 v25, 0xffff0000, v56
	v_lshlrev_b32_e32 v26, 16, v57
	v_and_b32_e32 v27, 0xffff0000, v57
	v_pk_fma_f32 v[28:29], v[20:21], v[72:73], v[28:29]
	v_pk_fma_f32 v[30:31], v[22:23], v[60:61], v[30:31]
	v_pk_mul_f32 v[24:25], v[28:29], v[24:25]
	v_pk_mul_f32 v[26:27], v[30:31], v[26:27]
	v_pk_mul_f32 v[28:29], v[8:9], v[88:89]
	v_pk_mul_f32 v[30:31], v[10:11], v[90:91]
	v_lshlrev_b32_e32 v76, 16, v62
	v_and_b32_e32 v77, 0xffff0000, v62
	v_lshlrev_b32_e32 v62, 16, v63
	v_and_b32_e32 v63, 0xffff0000, v63
	v_pk_fma_f32 v[30:31], v[2:3], v[80:81], v[30:31]
	v_pk_fma_f32 v[28:29], v[0:1], v[78:79], v[28:29]
	v_lshlrev_b32_e32 v56, 16, v58
	v_and_b32_e32 v57, 0xffff0000, v58
	v_lshlrev_b32_e32 v58, 16, v59
	v_and_b32_e32 v59, 0xffff0000, v59
	v_pk_fma_f32 v[28:29], v[16:17], v[76:77], v[28:29]
	v_pk_fma_f32 v[30:31], v[18:19], v[62:63], v[30:31]
	v_pk_mul_f32 v[28:29], v[28:29], v[56:57]
	v_pk_mul_f32 v[30:31], v[30:31], v[58:59]
	v_cvt_pk_bf16_f32 v24, v24, v25
	v_cvt_pk_bf16_f32 v25, v26, v27
	v_cvt_pk_bf16_f32 v26, v28, v29
	s_waitcnt vmcnt(5)
	v_lshlrev_b32_e32 v28, 16, v42
	v_cvt_pk_bf16_f32 v27, v30, v31
	global_store_dwordx4 v[70:71], v[24:27], off offset:-2048
	v_and_b32_e32 v29, 0xffff0000, v42
	v_lshlrev_b32_e32 v30, 16, v43
	v_lshlrev_b32_e32 v24, 16, v40
	v_and_b32_e32 v25, 0xffff0000, v40
	v_lshlrev_b32_e32 v26, 16, v41
	v_and_b32_e32 v27, 0xffff0000, v41
	v_and_b32_e32 v31, 0xffff0000, v43
	v_pk_mul_f32 v[40:41], v[12:13], v[72:73]
	v_pk_mul_f32 v[42:43], v[14:15], v[60:61]
	v_lshlrev_b32_e32 v56, 16, v52
	v_and_b32_e32 v57, 0xffff0000, v52
	v_lshlrev_b32_e32 v58, 16, v53
	v_and_b32_e32 v59, 0xffff0000, v53
	v_pk_fma_f32 v[42:43], v[6:7], v[86:87], v[42:43]
	v_pk_fma_f32 v[40:41], v[4:5], v[82:83], v[40:41]
	v_pk_fma_f32 v[42:43], v[22:23], v[58:59], v[42:43]
	v_pk_fma_f32 v[40:41], v[20:21], v[56:57], v[40:41]
	v_pk_mul_f32 v[26:27], v[42:43], v[26:27]
	v_pk_mul_f32 v[24:25], v[40:41], v[24:25]
	v_pk_mul_f32 v[40:41], v[8:9], v[76:77]
	v_pk_mul_f32 v[42:43], v[10:11], v[62:63]
	v_lshlrev_b32_e32 v52, 16, v54
	v_and_b32_e32 v53, 0xffff0000, v54
	v_lshlrev_b32_e32 v54, 16, v55
	v_and_b32_e32 v55, 0xffff0000, v55
	v_pk_fma_f32 v[42:43], v[2:3], v[90:91], v[42:43]
	v_pk_fma_f32 v[40:41], v[0:1], v[88:89], v[40:41]
	v_pk_fma_f32 v[42:43], v[18:19], v[54:55], v[42:43]
	v_pk_fma_f32 v[40:41], v[16:17], v[52:53], v[40:41]
	v_pk_mul_f32 v[30:31], v[42:43], v[30:31]
	v_pk_mul_f32 v[28:29], v[40:41], v[28:29]
	v_cvt_pk_bf16_f32 v24, v24, v25
	v_cvt_pk_bf16_f32 v25, v26, v27
	v_lshlrev_b32_e32 v40, 16, v32
	v_cvt_pk_bf16_f32 v26, v28, v29
	v_cvt_pk_bf16_f32 v27, v30, v31
	global_store_dwordx4 v[66:67], v[24:27], off offset:-4096
	v_lshlrev_b32_e32 v28, 16, v50
	v_and_b32_e32 v29, 0xffff0000, v50
	v_lshlrev_b32_e32 v24, 16, v48
	v_and_b32_e32 v25, 0xffff0000, v48
	v_lshlrev_b32_e32 v26, 16, v49
	v_and_b32_e32 v27, 0xffff0000, v49
	v_lshlrev_b32_e32 v30, 16, v51
	v_and_b32_e32 v31, 0xffff0000, v51
	v_pk_mul_f32 v[48:49], v[12:13], v[56:57]
	v_pk_mul_f32 v[50:51], v[14:15], v[58:59]
	v_and_b32_e32 v41, 0xffff0000, v32
	v_lshlrev_b32_e32 v42, 16, v33
	v_and_b32_e32 v43, 0xffff0000, v33
	v_pk_fma_f32 v[50:51], v[6:7], v[60:61], v[50:51]
	v_pk_fma_f32 v[48:49], v[4:5], v[72:73], v[48:49]
	v_pk_fma_f32 v[50:51], v[22:23], v[42:43], v[50:51]
	v_pk_fma_f32 v[48:49], v[20:21], v[40:41], v[48:49]
	v_pk_mul_f32 v[26:27], v[50:51], v[26:27]
	v_pk_mul_f32 v[24:25], v[48:49], v[24:25]
	v_pk_mul_f32 v[48:49], v[8:9], v[52:53]
	v_pk_mul_f32 v[50:51], v[10:11], v[54:55]
	v_lshlrev_b32_e32 v32, 16, v34
	v_and_b32_e32 v33, 0xffff0000, v34
	v_lshlrev_b32_e32 v34, 16, v35
	v_and_b32_e32 v35, 0xffff0000, v35
	v_pk_fma_f32 v[50:51], v[2:3], v[62:63], v[50:51]
	v_pk_fma_f32 v[48:49], v[0:1], v[76:77], v[48:49]
	v_pk_fma_f32 v[50:51], v[18:19], v[34:35], v[50:51]
	v_pk_fma_f32 v[48:49], v[16:17], v[32:33], v[48:49]
	v_pk_mul_f32 v[30:31], v[50:51], v[30:31]
	v_pk_mul_f32 v[28:29], v[48:49], v[28:29]
	v_cvt_pk_bf16_f32 v24, v24, v25
	v_cvt_pk_bf16_f32 v25, v26, v27
	s_nop 0
	v_cvt_pk_bf16_f32 v26, v28, v29
	v_cvt_pk_bf16_f32 v27, v30, v31
	global_store_dwordx4 v[66:67], v[24:27], off offset:-2048
	s_cbranch_vccnz .LBB0_652
	global_store_dwordx4 v[68:69], v[40:43], off
	global_store_dwordx4 v[68:69], v[32:35], off offset:16
